# up GEMM: units of the 17th row tile per sequence (34 live rows) skip the MFMA clusters of rows that are never stored (waves wr=1 all, wr=0 the ai=1 half)
# baseline (speedup 1.0000x reference)
; #define PG8_WAIT_V(n) asm volatile("s_waitcnt vmcnt(" #n ")" ::: "memory")
; template <class Epi, class Sched, bool ALIGN_EPI = false, bool SP2 = false>
; __device__ __forceinline__ void gemm_phase(PG8_LAS unsigned char* lds, const Gemm g, const Sched& S, const Epi& E) {
;     ...
;     f32x4 acc[2][2][4][2];
; #pragma unroll
;     for (int a = 0; a < 2; ++a)
; #pragma unroll
;         for (int b = 0; b < 2; ++b)
; #pragma unroll
;             for (int m = 0; m < 4; ++m)
; #pragma unroll
;                 for (int n = 0; n < 2; ++n) acc[a][b][m][n] = (f32x4){0.f, 0.f, 0.f, 0.f};
;     bf16x8 At[4][2], B0[2][2], B1[2][2];
;     const char* cA = (const char*)g.A + (long)S.a_row(cur) * (long)(K * 2); const char* cB = (const char*)g.Bt + (size_t)cur.pn * tstep;
;     S.a_ready(cur);
;     if constexpr (SP2) {
;         PG8_STAGE(PG8_SB(0, 0), cB, voffB); PG8_STAGE(PG8_SB(0, 1), cB + hstep, voffB); PG8_STAGE(PG8_SA(0, 0), cA, voffA); PG8_STAGE(PG8_SA(0, 1), cA + hstep, voffA);
;         if (wr == 1) PG8_BAR;
;         PG8_WAIT_V(2); PG8_BAR;
;         PG8_STAGE(PG8_SB(1, 0), cB + kstep, voffB); PG8_STAGE(PG8_SA(1, 0), cA + kstep, voffA); PG8_STAGE(PG8_SB(1, 1), cB + hstep + kstep, voffB);
;         PG8_WAIT_V(6); PG8_BAR;
;     } else {
;         PG8_STAGE(PG8_SB(0, 0), cB, voffB); PG8_STAGE(PG8_SA(0, 0), cA, voffA); PG8_STAGE(PG8_SB(0, 1), cB + hstep, voffB); PG8_STAGE(PG8_SA(0, 1), cA + hstep, voffA);
;         if (wr == 1) PG8_BAR;
;         PG8_WAIT_V(4); PG8_BAR;
;         PG8_STAGE(PG8_SB(1, 0), cB + kstep, voffB); PG8_STAGE(PG8_SA(1, 0), cA + kstep, voffA); PG8_STAGE(PG8_SB(1, 1), cB + hstep + kstep, voffB);
;         PG8_WAIT_V(6); PG8_BAR;
;     }
;     for (;;) {
;         const bool has_next = S.next(ui + 1, nxt);
;         const char* nA = has_next ? (const char*)g.A + (long)S.a_row(nxt) * (long)(K * 2) : cA; const char* nB = has_next ? (const char*)g.Bt + (size_t)nxt.pn * tstep : cB;
;         for (int t = 0; t < nt; t += 2) {
;             const bool last = (t == nt - 2);
;             const char* a1 = cA + (size_t)(t + 1) * kstep;
;             const char* a2 = last ? nA : cA + (size_t)(t + 2) * kstep; const char* b2 = last ? nB : cB + (size_t)(t + 2) * kstep;
;             const char* a3 = a2 + kstep; const char* b3 = b2 + kstep;
;             if (last && has_next) S.a_ready(nxt);
;             if constexpr (SP2) {
.LBB0_888:
	s_ashr_i32 s59, s58, 31
	s_lshl_b64 s[62:63], s[58:59], 20
	s_add_u32 s62, s38, s62
	s_addc_u32 s63, s39, s63
	s_and_b64 s[0:1], s[0:1], exec
	s_cselect_b32 s59, s63, s67
	s_cselect_b32 s65, s62, s66
	s_add_u32 s0, s76, 0x80080
	s_addc_u32 s1, s77, 0
	s_add_u32 s72, s66, 0x100
	v_mov_b32_e32 v0, 0
	s_addc_u32 s73, s67, 0
	s_mov_b32 s74, -2
	s_cmp_lg_u32 s92, 0
	s_cselect_b32 s101, 3, 2
	s_cmp_eq_u32 s71, 16
	s_cselect_b32 s100, s101, 0
	s_cmp_eq_u32 s71, 33
	s_cselect_b32 s101, s101, s100
	v_mov_b32_e32 v1, v0
	v_mov_b32_e32 v2, v0
	v_mov_b32_e32 v3, v0
	v_mov_b32_e32 v64, v0
	v_mov_b32_e32 v65, v0
	v_mov_b32_e32 v66, v0
	v_mov_b32_e32 v67, v0
	v_mov_b32_e32 v8, v0
	v_mov_b32_e32 v9, v0
	v_mov_b32_e32 v10, v0
	v_mov_b32_e32 v11, v0
	v_mov_b32_e32 v104, v0
	v_mov_b32_e32 v105, v0
	v_mov_b32_e32 v106, v0
	v_mov_b32_e32 v107, v0
	v_mov_b32_e32 v16, v0
	v_mov_b32_e32 v17, v0
	v_mov_b32_e32 v18, v0
	v_mov_b32_e32 v19, v0
	v_mov_b32_e32 v112, v0
	v_mov_b32_e32 v113, v0
	v_mov_b32_e32 v114, v0
	v_mov_b32_e32 v115, v0
	v_mov_b32_e32 v24, v0
	v_mov_b32_e32 v25, v0
	v_mov_b32_e32 v26, v0
	v_mov_b32_e32 v27, v0
	v_mov_b32_e32 v140, v0
	v_mov_b32_e32 v141, v0
	v_mov_b32_e32 v142, v0
	v_mov_b32_e32 v143, v0
	v_mov_b32_e32 v4, v0
	v_mov_b32_e32 v5, v0
	v_mov_b32_e32 v6, v0
	v_mov_b32_e32 v7, v0
	v_mov_b32_e32 v76, v0
	v_mov_b32_e32 v77, v0
	v_mov_b32_e32 v78, v0
	v_mov_b32_e32 v79, v0
	v_mov_b32_e32 v12, v0
	v_mov_b32_e32 v13, v0
	v_mov_b32_e32 v14, v0
	v_mov_b32_e32 v15, v0
	v_mov_b32_e32 v108, v0
	v_mov_b32_e32 v109, v0
	v_mov_b32_e32 v110, v0
	v_mov_b32_e32 v111, v0
	v_mov_b32_e32 v20, v0
	v_mov_b32_e32 v21, v0
	v_mov_b32_e32 v22, v0
	v_mov_b32_e32 v23, v0
	s_waitcnt vmcnt(0)
	v_mov_b32_e32 v116, v0
	v_mov_b32_e32 v117, v0
	v_mov_b32_e32 v118, v0
	v_mov_b32_e32 v119, v0
	v_mov_b32_e32 v28, v0
	v_mov_b32_e32 v29, v0
	v_mov_b32_e32 v30, v0
	v_mov_b32_e32 v31, v0
	v_mov_b32_e32 v156, v0
	v_mov_b32_e32 v157, v0
	v_mov_b32_e32 v158, v0
	v_mov_b32_e32 v159, v0
	v_mov_b32_e32 v32, v0
	v_mov_b32_e32 v33, v0
	v_mov_b32_e32 v34, v0
	v_mov_b32_e32 v35, v0
	v_mov_b32_e32 v68, v0
	v_mov_b32_e32 v69, v0
	v_mov_b32_e32 v70, v0
	v_mov_b32_e32 v71, v0
	v_mov_b32_e32 v40, v0
	v_mov_b32_e32 v41, v0
	v_mov_b32_e32 v42, v0
	v_mov_b32_e32 v43, v0
	v_mov_b32_e32 v80, v0
	v_mov_b32_e32 v81, v0
	v_mov_b32_e32 v82, v0
	v_mov_b32_e32 v83, v0
	v_mov_b32_e32 v48, v0
	v_mov_b32_e32 v49, v0
	v_mov_b32_e32 v50, v0
	v_mov_b32_e32 v51, v0
	v_mov_b32_e32 v88, v0
	v_mov_b32_e32 v89, v0
	v_mov_b32_e32 v90, v0
	v_mov_b32_e32 v91, v0
	v_mov_b32_e32 v56, v0
	v_mov_b32_e32 v57, v0
	v_mov_b32_e32 v58, v0
	v_mov_b32_e32 v59, v0
	v_mov_b32_e32 v96, v0
	v_mov_b32_e32 v97, v0
	v_mov_b32_e32 v98, v0
	v_mov_b32_e32 v99, v0
	v_mov_b32_e32 v36, v0
	v_mov_b32_e32 v37, v0
	v_mov_b32_e32 v38, v0
	v_mov_b32_e32 v39, v0
	v_mov_b32_e32 v72, v0
	v_mov_b32_e32 v73, v0
	v_mov_b32_e32 v74, v0
	v_mov_b32_e32 v75, v0
	v_mov_b32_e32 v44, v0
	v_mov_b32_e32 v45, v0
	v_mov_b32_e32 v46, v0
	v_mov_b32_e32 v47, v0
	v_mov_b32_e32 v84, v0
	v_mov_b32_e32 v85, v0
	v_mov_b32_e32 v86, v0
	v_mov_b32_e32 v87, v0
	v_mov_b32_e32 v52, v0
	v_mov_b32_e32 v53, v0
	v_mov_b32_e32 v54, v0
	v_mov_b32_e32 v55, v0
	v_mov_b32_e32 v92, v0
	v_mov_b32_e32 v93, v0
	v_mov_b32_e32 v94, v0
	v_mov_b32_e32 v95, v0
	v_mov_b32_e32 v60, v0
	v_mov_b32_e32 v61, v0
	v_mov_b32_e32 v62, v0
	v_mov_b32_e32 v63, v0
	v_mov_b32_e32 v100, v0
	v_mov_b32_e32 v101, v0
	v_mov_b32_e32 v102, v0
	v_mov_b32_e32 v103, v0
.LBB0_889:
	ds_read_b128 v[120:123], v221
	ds_read_b128 v[124:127], v221 offset:1024
	ds_read_b128 v[128:131], v221 offset:2048
	ds_read_b128 v[132:135], v221 offset:3072
	ds_read_b128 v[136:139], v222
	ds_read_b128 v[144:147], v222 offset:1024
	ds_read_b128 v[148:151], v222 offset:2048
	ds_read_b128 v[152:155], v222 offset:3072
	s_add_u32 s66, s0, 0xfff80080
	s_addc_u32 s67, s1, -1
	s_cmp_eq_u32 s74, 28
	s_cselect_b32 s77, s61, s67
	s_cselect_b32 s76, s60, s66
	s_cselect_b32 s67, s59, s73
	s_cselect_b32 s66, s65, s72
	v_lshl_add_u64 v[228:229], s[0:1], 0, v[184:185]
	s_add_i32 m0, s94, 0xc000
	ds_read_b128 v[160:163], v223
	ds_read_b128 v[164:167], v223 offset:1024
	ds_read_b128 v[168:171], v223 offset:2048
	ds_read_b128 v[172:175], v223 offset:3072
	ds_read_b128 v[192:195], v223 offset:4096
	ds_read_b128 v[196:199], v223 offset:5120
	ds_read_b128 v[200:203], v223 offset:6144
	ds_read_b128 v[204:207], v223 offset:7168
	global_load_lds_dwordx4 v[228:229], off
	v_lshl_add_u64 v[228:229], s[0:1], 0, v[186:187]
	s_add_i32 m0, s94, 0xe000
	s_nop 0
	global_load_lds_dwordx4 v[228:229], off
	s_waitcnt vmcnt(8)
	s_waitcnt lgkmcnt(0)
	s_barrier
	s_setprio 1
	s_bitcmp1_b32 s101, 0
	s_cbranch_scc1 .Lup_skip_0
	s_waitcnt lgkmcnt(0)
	v_mfma_f32_16x16x32_bf16 v[100:103], v[120:123], v[160:163], v[100:103]
	v_mfma_f32_16x16x32_bf16 v[60:63], v[128:131], v[160:163], v[60:63]
	v_mfma_f32_16x16x32_bf16 v[92:95], v[120:123], v[168:171], v[92:95]
	v_mfma_f32_16x16x32_bf16 v[52:55], v[128:131], v[168:171], v[52:55]
	v_mfma_f32_16x16x32_bf16 v[84:87], v[120:123], v[192:195], v[84:87]
	v_mfma_f32_16x16x32_bf16 v[44:47], v[128:131], v[192:195], v[44:47]
	v_mfma_f32_16x16x32_bf16 v[72:75], v[120:123], v[200:203], v[72:75]
	v_mfma_f32_16x16x32_bf16 v[36:39], v[128:131], v[200:203], v[36:39]
	v_mfma_f32_16x16x32_bf16 v[100:103], v[124:127], v[164:167], v[100:103]
	v_mfma_f32_16x16x32_bf16 v[60:63], v[132:135], v[164:167], v[60:63]
	v_mfma_f32_16x16x32_bf16 v[92:95], v[124:127], v[172:175], v[92:95]
	v_mfma_f32_16x16x32_bf16 v[52:55], v[132:135], v[172:175], v[52:55]
	v_mfma_f32_16x16x32_bf16 v[84:87], v[124:127], v[196:199], v[84:87]
	v_mfma_f32_16x16x32_bf16 v[44:47], v[132:135], v[196:199], v[44:47]
	v_mfma_f32_16x16x32_bf16 v[72:75], v[124:127], v[204:207], v[72:75]
	v_mfma_f32_16x16x32_bf16 v[36:39], v[132:135], v[204:207], v[36:39]
; #define PG8_STAGE(bufoff, gbase, voff) do { _Pragma("unroll") for (int _i = 0; _i < 2; ++_i) \
;         __builtin_amdgcn_global_load_lds((const unsigned*)((const char*)(gbase) + (voff)[_i]), (PG8_LAS unsigned*)(lds + (bufoff) + ldsw + _i * 8192), 16, 0, 0); } while (0)
; #define PG8_LDA(dst, b, h) do { _Pragma("unroll") for (int m = 0; m < 4; ++m) _Pragma("unroll") for (int k = 0; k < 2; ++k) dst[m][k] = *(const PG8_LAS bf16x8*)(lds + PG8_SA(b, h) + aoff + m * 2048 + k * 1024); } while (0)
; #define PG8_MMA(ai, bj, At, Bt) do { __builtin_amdgcn_s_setprio(1); _Pragma("unroll") for (int m = 0; m < 4; ++m) _Pragma("unroll") for (int n = 0; n < 2; ++n) _Pragma("unroll") for (int k = 0; k < 2; ++k) \
;         acc[ai][bj][m][n] = __builtin_amdgcn_mfma_f32_16x16x32_bf16(Bt[n][k], At[m][k], acc[ai][bj][m][n], 0, 0, 0); __builtin_amdgcn_s_setprio(0); } while (0)
; #define PG8_WAIT_V(n) asm volatile("s_waitcnt vmcnt(" #n ")" ::: "memory")
; #define PG8_WAIT_L(n) asm volatile("s_waitcnt lgkmcnt(" #n ")" ::: "memory")
; #define PG8_BAR __builtin_amdgcn_s_barrier()
; #define PG8_SCHED __builtin_amdgcn_sched_barrier(0)
; template <class Epi, class Sched, bool ALIGN_EPI = false, bool SP2 = false>
; __device__ __forceinline__ void gemm_phase(PG8_LAS unsigned char* lds, const Gemm g, const Sched& S, const Epi& E) {
;     ...
;             PG8_WAIT_V(8); PG8_WAIT_L(0); PG8_BAR; PG8_MMA(0, 0, At, B0); PG8_MMA(0, 1, At, B1); PG8_BAR; PG8_SCHED;
;             PG8_LDA(At, 0, 1); PG8_STAGE(PG8_SB(0, 0), b2, voffB); PG8_STAGE(PG8_SB(0, 1), b2 + hstep, voffB); PG8_STAGE(PG8_SA(0, 0), a2, voffA);
;             PG8_WAIT_V(8); PG8_WAIT_L(0); PG8_BAR; PG8_MMA(1, 0, At, B0); PG8_MMA(1, 1, At, B1); PG8_BAR; PG8_SCHED;
.Lup_skip_0:
	s_setprio 0
	s_setprio 1
	s_bitcmp1_b32 s101, 0
	s_cbranch_scc1 .Lup_skip_1
	v_mfma_f32_16x16x32_bf16 v[96:99], v[136:139], v[160:163], v[96:99]
	v_mfma_f32_16x16x32_bf16 v[56:59], v[148:151], v[160:163], v[56:59]
	v_mfma_f32_16x16x32_bf16 v[88:91], v[136:139], v[168:171], v[88:91]
	v_mfma_f32_16x16x32_bf16 v[48:51], v[148:151], v[168:171], v[48:51]
	v_mfma_f32_16x16x32_bf16 v[80:83], v[136:139], v[192:195], v[80:83]
	v_mfma_f32_16x16x32_bf16 v[40:43], v[148:151], v[192:195], v[40:43]
	v_mfma_f32_16x16x32_bf16 v[68:71], v[136:139], v[200:203], v[68:71]
	v_mfma_f32_16x16x32_bf16 v[32:35], v[148:151], v[200:203], v[32:35]
	v_mfma_f32_16x16x32_bf16 v[96:99], v[144:147], v[164:167], v[96:99]
	v_mfma_f32_16x16x32_bf16 v[56:59], v[152:155], v[164:167], v[56:59]
	v_mfma_f32_16x16x32_bf16 v[88:91], v[144:147], v[172:175], v[88:91]
	v_mfma_f32_16x16x32_bf16 v[48:51], v[152:155], v[172:175], v[48:51]
	v_mfma_f32_16x16x32_bf16 v[80:83], v[144:147], v[196:199], v[80:83]
	v_mfma_f32_16x16x32_bf16 v[40:43], v[152:155], v[196:199], v[40:43]
	v_mfma_f32_16x16x32_bf16 v[68:71], v[144:147], v[204:207], v[68:71]
	v_mfma_f32_16x16x32_bf16 v[32:35], v[152:155], v[204:207], v[32:35]
.Lup_skip_1:
	s_setprio 0
	s_barrier
	s_add_i32 s75, s90, s93
	v_lshl_add_u64 v[232:233], s[66:67], 0, v[178:179]
	s_mov_b32 m0, s75
	ds_read_b128 v[160:163], v223 offset:16384
	ds_read_b128 v[164:167], v223 offset:17408
	ds_read_b128 v[168:171], v223 offset:18432
	ds_read_b128 v[172:175], v223 offset:19456
	ds_read_b128 v[192:195], v223 offset:20480
	ds_read_b128 v[196:199], v223 offset:21504
	ds_read_b128 v[200:203], v223 offset:22528
	ds_read_b128 v[204:207], v223 offset:23552
	global_load_lds_dwordx4 v[232:233], off
	s_add_i32 m0, s75, 0x2000
	s_add_u32 s78, s66, 0x80000
	v_lshl_add_u64 v[234:235], s[66:67], 0, v[182:183]
	s_addc_u32 s79, s67, 0
	s_add_i32 s75, s3, s93
	global_load_lds_dwordx4 v[234:235], off
	v_lshl_add_u64 v[228:229], s[78:79], 0, v[178:179]
	s_mov_b32 m0, s75
	v_lshl_add_u64 v[236:237], s[76:77], 0, v[176:177]
	global_load_lds_dwordx4 v[228:229], off
	v_lshl_add_u64 v[228:229], s[78:79], 0, v[182:183]
	s_add_i32 m0, s75, 0x2000
	v_lshl_add_u64 v[238:239], s[76:77], 0, v[180:181]
	global_load_lds_dwordx4 v[228:229], off
	s_mov_b32 m0, s94
	s_nop 0
	global_load_lds_dwordx4 v[236:237], off
	s_mov_b32 m0, s95
	s_nop 0
	global_load_lds_dwordx4 v[238:239], off
	s_waitcnt vmcnt(8)
	s_waitcnt lgkmcnt(0)
	s_barrier
	s_setprio 1
	s_bitcmp1_b32 s101, 1
	s_cbranch_scc1 .Lup_skip_2
	s_waitcnt lgkmcnt(0)
	v_mfma_f32_16x16x32_bf16 v[156:159], v[120:123], v[160:163], v[156:159]
	v_mfma_f32_16x16x32_bf16 v[28:31], v[128:131], v[160:163], v[28:31]
	v_mfma_f32_16x16x32_bf16 v[116:119], v[120:123], v[168:171], v[116:119]
	v_mfma_f32_16x16x32_bf16 v[20:23], v[128:131], v[168:171], v[20:23]
	v_mfma_f32_16x16x32_bf16 v[108:111], v[120:123], v[192:195], v[108:111]
	v_mfma_f32_16x16x32_bf16 v[12:15], v[128:131], v[192:195], v[12:15]
	v_mfma_f32_16x16x32_bf16 v[76:79], v[120:123], v[200:203], v[76:79]
	v_mfma_f32_16x16x32_bf16 v[4:7], v[128:131], v[200:203], v[4:7]
	v_mfma_f32_16x16x32_bf16 v[156:159], v[124:127], v[164:167], v[156:159]
	v_mfma_f32_16x16x32_bf16 v[28:31], v[132:135], v[164:167], v[28:31]
	v_mfma_f32_16x16x32_bf16 v[116:119], v[124:127], v[172:175], v[116:119]
	v_mfma_f32_16x16x32_bf16 v[20:23], v[132:135], v[172:175], v[20:23]
	v_mfma_f32_16x16x32_bf16 v[108:111], v[124:127], v[196:199], v[108:111]
	v_mfma_f32_16x16x32_bf16 v[12:15], v[132:135], v[196:199], v[12:15]
	v_mfma_f32_16x16x32_bf16 v[76:79], v[124:127], v[204:207], v[76:79]
	v_mfma_f32_16x16x32_bf16 v[4:7], v[132:135], v[204:207], v[4:7]
.Lup_skip_2:
	s_setprio 0
	s_setprio 1
	s_bitcmp1_b32 s101, 1
	s_cbranch_scc1 .Lup_skip_3
	v_mfma_f32_16x16x32_bf16 v[24:27], v[148:151], v[160:163], v[24:27]
	v_mfma_f32_16x16x32_bf16 v[112:115], v[136:139], v[168:171], v[112:115]
	v_mfma_f32_16x16x32_bf16 v[16:19], v[148:151], v[168:171], v[16:19]
	v_mfma_f32_16x16x32_bf16 v[104:107], v[136:139], v[192:195], v[104:107]
	v_mfma_f32_16x16x32_bf16 v[8:11], v[148:151], v[192:195], v[8:11]
	v_mfma_f32_16x16x32_bf16 v[64:67], v[136:139], v[200:203], v[64:67]
	v_mfma_f32_16x16x32_bf16 v[0:3], v[148:151], v[200:203], v[0:3]
	v_mfma_f32_16x16x32_bf16 v[120:123], v[136:139], v[160:163], v[140:143]
	v_mfma_f32_16x16x32_bf16 v[24:27], v[152:155], v[164:167], v[24:27]
	v_mfma_f32_16x16x32_bf16 v[112:115], v[144:147], v[172:175], v[112:115]
	v_mfma_f32_16x16x32_bf16 v[16:19], v[152:155], v[172:175], v[16:19]
	v_mfma_f32_16x16x32_bf16 v[104:107], v[144:147], v[196:199], v[104:107]
	v_mfma_f32_16x16x32_bf16 v[8:11], v[152:155], v[196:199], v[8:11]
	v_mfma_f32_16x16x32_bf16 v[64:67], v[144:147], v[204:207], v[64:67]
	v_mfma_f32_16x16x32_bf16 v[0:3], v[152:155], v[204:207], v[0:3]
	v_mfma_f32_16x16x32_bf16 v[120:123], v[144:147], v[164:167], v[120:123]
; #define PG8_STAGE(bufoff, gbase, voff) do { _Pragma("unroll") for (int _i = 0; _i < 2; ++_i) \
;         __builtin_amdgcn_global_load_lds((const unsigned*)((const char*)(gbase) + (voff)[_i]), (PG8_LAS unsigned*)(lds + (bufoff) + ldsw + _i * 8192), 16, 0, 0); } while (0)
; #define PG8_LDA(dst, b, h) do { _Pragma("unroll") for (int m = 0; m < 4; ++m) _Pragma("unroll") for (int k = 0; k < 2; ++k) dst[m][k] = *(const PG8_LAS bf16x8*)(lds + PG8_SA(b, h) + aoff + m * 2048 + k * 1024); } while (0)
; #define PG8_LDB(dst, b, h) do { _Pragma("unroll") for (int n = 0; n < 2; ++n) _Pragma("unroll") for (int k = 0; k < 2; ++k) dst[n][k] = *(const PG8_LAS bf16x8*)(lds + PG8_SB(b, h) + boff + n * 2048 + k * 1024); } while (0)
; #define PG8_MMA(ai, bj, At, Bt) do { __builtin_amdgcn_s_setprio(1); _Pragma("unroll") for (int m = 0; m < 4; ++m) _Pragma("unroll") for (int n = 0; n < 2; ++n) _Pragma("unroll") for (int k = 0; k < 2; ++k) \
;         acc[ai][bj][m][n] = __builtin_amdgcn_mfma_f32_16x16x32_bf16(Bt[n][k], At[m][k], acc[ai][bj][m][n], 0, 0, 0); __builtin_amdgcn_s_setprio(0); } while (0)
; #define PG8_WAIT_V(n) asm volatile("s_waitcnt vmcnt(" #n ")" ::: "memory")
; #define PG8_WAIT_L(n) asm volatile("s_waitcnt lgkmcnt(" #n ")" ::: "memory")
; #define PG8_BAR __builtin_amdgcn_s_barrier()
; #define PG8_SCHED __builtin_amdgcn_sched_barrier(0)
; template <class Epi, class Sched, bool ALIGN_EPI = false, bool SP2 = false>
; __device__ __forceinline__ void gemm_phase(PG8_LAS unsigned char* lds, const Gemm g, const Sched& S, const Epi& E) {
;     ...
;             PG8_LDB(B0, 1, 0); PG8_LDB(B1, 1, 1); PG8_SCHED; PG8_LDA(At, 1, 0); PG8_STAGE(PG8_SA(0, 1), a2 + hstep, voffA);
;             PG8_WAIT_V(8); PG8_WAIT_L(0); PG8_BAR; PG8_MMA(0, 0, At, B0); PG8_MMA(0, 1, At, B1); PG8_BAR; PG8_SCHED;
.Lup_skip_3:
	s_setprio 0
	s_barrier
	s_add_i32 s75, 0, 0x18000
	s_add_i32 s78, 0, 0x1c000
	v_add_u32_e32 v136, s75, v209
	v_add_u32_e32 v140, s78, v209
	ds_read_b128 v[124:127], v136
	ds_read_b128 v[128:131], v136 offset:1024
	ds_read_b128 v[132:135], v136 offset:2048
	ds_read_b128 v[136:139], v136 offset:3072
	ds_read_b128 v[144:147], v140
	ds_read_b128 v[148:151], v140 offset:1024
	ds_read_b128 v[152:155], v140 offset:2048
	ds_read_b128 v[160:163], v140 offset:3072
	s_add_u32 s76, s76, 0x80000
	s_addc_u32 s77, s77, 0
	s_mov_b32 m0, s96
	v_lshl_add_u64 v[228:229], s[76:77], 0, v[176:177]
	ds_read_b128 v[140:143], v223 offset:32768
	ds_read_b128 v[164:167], v223 offset:33792
	ds_read_b128 v[168:171], v223 offset:34816
	ds_read_b128 v[172:175], v223 offset:35840
	ds_read_b128 v[192:195], v223 offset:36864
	ds_read_b128 v[196:199], v223 offset:37888
	ds_read_b128 v[200:203], v223 offset:38912
	ds_read_b128 v[204:207], v223 offset:39936
	global_load_lds_dwordx4 v[228:229], off
	v_lshl_add_u64 v[228:229], s[76:77], 0, v[180:181]
	s_mov_b32 m0, s97
	s_nop 0
	global_load_lds_dwordx4 v[228:229], off
	s_waitcnt vmcnt(8)
	s_waitcnt lgkmcnt(0)
	s_barrier
	s_setprio 1
	s_bitcmp1_b32 s101, 0
	s_cbranch_scc1 .Lup_skip_4
	s_waitcnt lgkmcnt(0)
	v_mfma_f32_16x16x32_bf16 v[100:103], v[124:127], v[140:143], v[100:103]
	v_mfma_f32_16x16x32_bf16 v[60:63], v[132:135], v[140:143], v[60:63]
	v_mfma_f32_16x16x32_bf16 v[92:95], v[124:127], v[168:171], v[92:95]
	v_mfma_f32_16x16x32_bf16 v[52:55], v[132:135], v[168:171], v[52:55]
	v_mfma_f32_16x16x32_bf16 v[84:87], v[124:127], v[192:195], v[84:87]
	v_mfma_f32_16x16x32_bf16 v[44:47], v[132:135], v[192:195], v[44:47]
	v_mfma_f32_16x16x32_bf16 v[72:75], v[124:127], v[200:203], v[72:75]
	v_mfma_f32_16x16x32_bf16 v[36:39], v[132:135], v[200:203], v[36:39]
	v_mfma_f32_16x16x32_bf16 v[100:103], v[128:131], v[164:167], v[100:103]
	v_mfma_f32_16x16x32_bf16 v[60:63], v[136:139], v[164:167], v[60:63]
	v_mfma_f32_16x16x32_bf16 v[92:95], v[128:131], v[172:175], v[92:95]
	v_mfma_f32_16x16x32_bf16 v[52:55], v[136:139], v[172:175], v[52:55]
	v_mfma_f32_16x16x32_bf16 v[84:87], v[128:131], v[196:199], v[84:87]
	v_mfma_f32_16x16x32_bf16 v[44:47], v[136:139], v[196:199], v[44:47]
	v_mfma_f32_16x16x32_bf16 v[72:75], v[128:131], v[204:207], v[72:75]
	v_mfma_f32_16x16x32_bf16 v[36:39], v[136:139], v[204:207], v[36:39]
.Lup_skip_4:
	s_setprio 0
	s_setprio 1
	s_bitcmp1_b32 s101, 0
	s_cbranch_scc1 .Lup_skip_5
	v_mfma_f32_16x16x32_bf16 v[96:99], v[144:147], v[140:143], v[96:99]
	v_mfma_f32_16x16x32_bf16 v[56:59], v[152:155], v[140:143], v[56:59]
	v_mfma_f32_16x16x32_bf16 v[88:91], v[144:147], v[168:171], v[88:91]
	v_mfma_f32_16x16x32_bf16 v[48:51], v[152:155], v[168:171], v[48:51]
	v_mfma_f32_16x16x32_bf16 v[80:83], v[144:147], v[192:195], v[80:83]
	v_mfma_f32_16x16x32_bf16 v[40:43], v[152:155], v[192:195], v[40:43]
	v_mfma_f32_16x16x32_bf16 v[68:71], v[144:147], v[200:203], v[68:71]
	v_mfma_f32_16x16x32_bf16 v[32:35], v[152:155], v[200:203], v[32:35]
	v_mfma_f32_16x16x32_bf16 v[96:99], v[148:151], v[164:167], v[96:99]
	v_mfma_f32_16x16x32_bf16 v[56:59], v[160:163], v[164:167], v[56:59]
	v_mfma_f32_16x16x32_bf16 v[88:91], v[148:151], v[172:175], v[88:91]
	v_mfma_f32_16x16x32_bf16 v[48:51], v[160:163], v[172:175], v[48:51]
	v_mfma_f32_16x16x32_bf16 v[80:83], v[148:151], v[196:199], v[80:83]
	v_mfma_f32_16x16x32_bf16 v[40:43], v[160:163], v[196:199], v[40:43]
	v_mfma_f32_16x16x32_bf16 v[68:71], v[148:151], v[204:207], v[68:71]
	v_mfma_f32_16x16x32_bf16 v[32:35], v[160:163], v[204:207], v[32:35]
; #define PG8_STAGE(bufoff, gbase, voff) do { _Pragma("unroll") for (int _i = 0; _i < 2; ++_i) \
;         __builtin_amdgcn_global_load_lds((const unsigned*)((const char*)(gbase) + (voff)[_i]), (PG8_LAS unsigned*)(lds + (bufoff) + ldsw + _i * 8192), 16, 0, 0); } while (0)
; #define PG8_LDA(dst, b, h) do { _Pragma("unroll") for (int m = 0; m < 4; ++m) _Pragma("unroll") for (int k = 0; k < 2; ++k) dst[m][k] = *(const PG8_LAS bf16x8*)(lds + PG8_SA(b, h) + aoff + m * 2048 + k * 1024); } while (0)
; #define PG8_LDB(dst, b, h) do { _Pragma("unroll") for (int n = 0; n < 2; ++n) _Pragma("unroll") for (int k = 0; k < 2; ++k) dst[n][k] = *(const PG8_LAS bf16x8*)(lds + PG8_SB(b, h) + boff + n * 2048 + k * 1024); } while (0)
; template <class Epi, class Sched, bool ALIGN_EPI = false, bool SP2 = false>
; __device__ __forceinline__ void gemm_phase(PG8_LAS unsigned char* lds, const Gemm g, const Sched& S, const Epi& E) {
;     ...
;         for (int t = 0; t < nt; t += 2) {
;             const bool last = (t == nt - 2);
;             const char* a1 = cA + (size_t)(t + 1) * kstep;
;             const char* a2 = last ? nA : cA + (size_t)(t + 2) * kstep; const char* b2 = last ? nB : cB + (size_t)(t + 2) * kstep;
;             const char* a3 = a2 + kstep; const char* b3 = b2 + kstep;
;             if (last && has_next) S.a_ready(nxt);
;             if constexpr (SP2) {
;             PG8_LDB(B0, 0, 0); PG8_LDB(B1, 0, 1); PG8_SCHED; PG8_LDA(At, 0, 0); PG8_STAGE(PG8_SA(1, 1), a1 + hstep, voffA);
;             PG8_WAIT_V(8); PG8_WAIT_L(0); PG8_BAR; PG8_MMA(0, 0, At, B0); PG8_MMA(0, 1, At, B1); PG8_BAR; PG8_SCHED;
;             PG8_LDA(At, 0, 1); PG8_STAGE(PG8_SB(0, 0), b2, voffB); PG8_STAGE(PG8_SB(0, 1), b2 + hstep, voffB); PG8_STAGE(PG8_SA(0, 0), a2, voffA);
;             PG8_WAIT_V(8); PG8_WAIT_L(0); PG8_BAR; PG8_MMA(1, 0, At, B0); PG8_MMA(1, 1, At, B1); PG8_BAR; PG8_SCHED;
;             PG8_LDB(B0, 1, 0); PG8_LDB(B1, 1, 1); PG8_SCHED; PG8_LDA(At, 1, 0); PG8_STAGE(PG8_SA(0, 1), a2 + hstep, voffA);
;             PG8_WAIT_V(8); PG8_WAIT_L(0); PG8_BAR; PG8_MMA(0, 0, At, B0); PG8_MMA(0, 1, At, B1); PG8_BAR; PG8_SCHED;
;             PG8_LDA(At, 1, 1); PG8_STAGE(PG8_SB(1, 0), b3, voffB); PG8_STAGE(PG8_SB(1, 1), b3 + hstep, voffB); PG8_STAGE(PG8_SA(1, 0), a3, voffA);
;             PG8_WAIT_V(8); PG8_WAIT_L(0); PG8_BAR; PG8_MMA(1, 0, At, B0); PG8_MMA(1, 1, At, B1); PG8_BAR; PG8_SCHED;
.Lup_skip_5:
	s_setprio 0
	s_barrier
	s_add_i32 s75, s75, s93
	v_lshl_add_u64 v[140:141], v[232:233], 0, s[44:45]
	s_mov_b32 m0, s75
	ds_read_b128 v[164:167], v223 offset:49152
	ds_read_b128 v[168:171], v223 offset:50176
	ds_read_b128 v[172:175], v223 offset:51200
	ds_read_b128 v[192:195], v223 offset:52224
	ds_read_b128 v[196:199], v223 offset:53248
	ds_read_b128 v[200:203], v223 offset:54272
	ds_read_b128 v[204:207], v223 offset:55296
	ds_read_b128 v[228:231], v223 offset:56320
	global_load_lds_dwordx4 v[140:141], off
	s_add_i32 m0, s75, 0x2000
	s_add_u32 s66, s66, 0x80080
	v_lshl_add_u64 v[140:141], v[234:235], 0, s[44:45]
	s_addc_u32 s67, s67, 0
	s_add_i32 s75, s78, s93
	global_load_lds_dwordx4 v[140:141], off
	v_lshl_add_u64 v[140:141], s[66:67], 0, v[178:179]
	s_mov_b32 m0, s75
	s_nop 0
	global_load_lds_dwordx4 v[140:141], off
	v_lshl_add_u64 v[140:141], s[66:67], 0, v[182:183]
	s_add_i32 m0, s75, 0x2000
	s_nop 0
	global_load_lds_dwordx4 v[140:141], off
	v_lshl_add_u64 v[140:141], v[236:237], 0, s[44:45]
	s_mov_b32 m0, s91
	s_nop 0
	global_load_lds_dwordx4 v[140:141], off
	v_lshl_add_u64 v[140:141], v[238:239], 0, s[44:45]
	s_mov_b32 m0, s24
	s_nop 0
	global_load_lds_dwordx4 v[140:141], off
	s_waitcnt vmcnt(8)
	s_waitcnt lgkmcnt(0)
	s_barrier
	s_setprio 1
	s_bitcmp1_b32 s101, 1
	s_cbranch_scc1 .Lup_skip_6
	s_waitcnt lgkmcnt(0)
	v_mfma_f32_16x16x32_bf16 v[140:143], v[124:127], v[164:167], v[156:159]
	v_mfma_f32_16x16x32_bf16 v[28:31], v[132:135], v[164:167], v[28:31]
	v_mfma_f32_16x16x32_bf16 v[116:119], v[124:127], v[172:175], v[116:119]
	v_mfma_f32_16x16x32_bf16 v[20:23], v[132:135], v[172:175], v[20:23]
	v_mfma_f32_16x16x32_bf16 v[108:111], v[124:127], v[196:199], v[108:111]
	v_mfma_f32_16x16x32_bf16 v[12:15], v[132:135], v[196:199], v[12:15]
	v_mfma_f32_16x16x32_bf16 v[76:79], v[124:127], v[204:207], v[76:79]
	v_mfma_f32_16x16x32_bf16 v[4:7], v[132:135], v[204:207], v[4:7]
	v_mfma_f32_16x16x32_bf16 v[156:159], v[128:131], v[168:171], v[140:143]
	v_mfma_f32_16x16x32_bf16 v[28:31], v[136:139], v[168:171], v[28:31]
	v_mfma_f32_16x16x32_bf16 v[116:119], v[128:131], v[192:195], v[116:119]
	v_mfma_f32_16x16x32_bf16 v[20:23], v[136:139], v[192:195], v[20:23]
	v_mfma_f32_16x16x32_bf16 v[108:111], v[128:131], v[200:203], v[108:111]
	v_mfma_f32_16x16x32_bf16 v[12:15], v[136:139], v[200:203], v[12:15]
	v_mfma_f32_16x16x32_bf16 v[76:79], v[128:131], v[228:231], v[76:79]
	v_mfma_f32_16x16x32_bf16 v[4:7], v[136:139], v[228:231], v[4:7]
.Lup_skip_6:
	s_setprio 0
	s_setprio 1
	s_bitcmp1_b32 s101, 1
	s_cbranch_scc1 .Lup_skip_7
	v_mfma_f32_16x16x32_bf16 v[120:123], v[144:147], v[164:167], v[120:123]
	v_mfma_f32_16x16x32_bf16 v[24:27], v[152:155], v[164:167], v[24:27]
	v_mfma_f32_16x16x32_bf16 v[112:115], v[144:147], v[172:175], v[112:115]
	v_mfma_f32_16x16x32_bf16 v[16:19], v[152:155], v[172:175], v[16:19]
	v_mfma_f32_16x16x32_bf16 v[104:107], v[144:147], v[196:199], v[104:107]
	v_mfma_f32_16x16x32_bf16 v[8:11], v[152:155], v[196:199], v[8:11]
	v_mfma_f32_16x16x32_bf16 v[64:67], v[144:147], v[204:207], v[64:67]
	v_mfma_f32_16x16x32_bf16 v[0:3], v[152:155], v[204:207], v[0:3]
	v_mfma_f32_16x16x32_bf16 v[140:143], v[148:151], v[168:171], v[120:123]
	v_mfma_f32_16x16x32_bf16 v[24:27], v[160:163], v[168:171], v[24:27]
	v_mfma_f32_16x16x32_bf16 v[112:115], v[148:151], v[192:195], v[112:115]
	v_mfma_f32_16x16x32_bf16 v[16:19], v[160:163], v[192:195], v[16:19]
	v_mfma_f32_16x16x32_bf16 v[104:107], v[148:151], v[200:203], v[104:107]
	v_mfma_f32_16x16x32_bf16 v[8:11], v[160:163], v[200:203], v[8:11]
	v_mfma_f32_16x16x32_bf16 v[64:67], v[148:151], v[228:231], v[64:67]
	v_mfma_f32_16x16x32_bf16 v[0:3], v[160:163], v[228:231], v[0:3]
.Lup_skip_7:
	s_setprio 0
	s_barrier
	s_add_i32 s74, s74, 2
	s_add_u32 s0, s0, 0x100
	s_addc_u32 s1, s1, 0
	s_add_u32 s72, s72, 0x100
	s_addc_u32 s73, s73, 0
	s_cmp_gt_u32 s74, 29
	s_cbranch_scc0 .LBB0_889
	v_readlane_b32 s0, v254, 13
	v_readlane_b32 s1, v254, 14
	s_and_b64 vcc, exec, s[0:1]
	s_cbranch_vccz .LBB0_892
	s_barrier
